# residual GEMMs: residual tile preloaded into the MFMA accumulators, epilogue stores only
# speedup vs baseline: 1.0013x; 1.0013x over previous
.LBB0_343:
	s_add_i32 s15, s55, -2
	s_add_u32 s48, s48, 0x80
	s_addc_u32 s49, s49, 0
	s_add_u32 s56, s50, 0x100
	s_addc_u32 s57, s51, 0
	s_mov_b32 s50, 0
	s_cmp_eq_u32 s58, 2
	s_cbranch_scc0 .Lrp_zero
	s_cmp_lt_i32 s88, 0
	s_cbranch_scc0 .Lrp_zero
	s_lshl_b32 s98, s54, 8
	s_add_i32 s98, s98, s86
	v_or_b32_e32 v130, s98, v188
	v_mov_b32_e32 v131, v1
	v_lshlrev_b64 v[130:131], 13, v[130:131]
	v_lshl_add_u64 v[130:131], s[18:19], 0, v[130:131]
	v_lshl_or_b32 v132, s23, 8, v225
	v_ashrrev_i32_e32 v133, 31, v132
	v_lshlrev_b64 v[132:133], 2, v[132:133]
	v_lshl_add_u64 v[134:135], v[130:131], 0, v[132:133]
	global_load_dwordx4 v[126:129], v[134:135], off
	global_load_dwordx4 v[122:125], v[134:135], off offset:64
	global_load_dwordx4 v[110:113], v[134:135], off offset:512
	global_load_dwordx4 v[106:109], v[134:135], off offset:576
	s_mov_b32 s98, 0x20000
	s_mov_b32 s99, 0
	v_lshl_add_u64 v[136:137], v[134:135], 0, s[98:99]
	global_load_dwordx4 v[118:121], v[136:137], off
	global_load_dwordx4 v[114:117], v[136:137], off offset:64
	global_load_dwordx4 v[94:97], v[136:137], off offset:512
	global_load_dwordx4 v[90:93], v[136:137], off offset:576
	s_mov_b32 s98, 0x40000
	s_mov_b32 s99, 0
	v_lshl_add_u64 v[136:137], v[134:135], 0, s[98:99]
	global_load_dwordx4 v[102:105], v[136:137], off
	global_load_dwordx4 v[98:101], v[136:137], off offset:64
	global_load_dwordx4 v[78:81], v[136:137], off offset:512
	global_load_dwordx4 v[74:77], v[136:137], off offset:576
	s_mov_b32 s98, 0x60000
	s_mov_b32 s99, 0
	v_lshl_add_u64 v[136:137], v[134:135], 0, s[98:99]
	global_load_dwordx4 v[86:89], v[136:137], off
	global_load_dwordx4 v[82:85], v[136:137], off offset:64
	global_load_dwordx4 v[70:73], v[136:137], off offset:512
	global_load_dwordx4 v[66:69], v[136:137], off offset:576
	s_mov_b32 s98, 0x100000
	s_mov_b32 s99, 0
	v_lshl_add_u64 v[136:137], v[134:135], 0, s[98:99]
	global_load_dwordx4 v[62:65], v[136:137], off
	global_load_dwordx4 v[58:61], v[136:137], off offset:64
	global_load_dwordx4 v[46:49], v[136:137], off offset:512
	global_load_dwordx4 v[42:45], v[136:137], off offset:576
	s_mov_b32 s98, 0x120000
	s_mov_b32 s99, 0
	v_lshl_add_u64 v[136:137], v[134:135], 0, s[98:99]
	global_load_dwordx4 v[54:57], v[136:137], off
	global_load_dwordx4 v[50:53], v[136:137], off offset:64
	global_load_dwordx4 v[30:33], v[136:137], off offset:512
	global_load_dwordx4 v[26:29], v[136:137], off offset:576
	s_mov_b32 s98, 0x140000
	s_mov_b32 s99, 0
	v_lshl_add_u64 v[136:137], v[134:135], 0, s[98:99]
	global_load_dwordx4 v[38:41], v[136:137], off
	global_load_dwordx4 v[34:37], v[136:137], off offset:64
	global_load_dwordx4 v[14:17], v[136:137], off offset:512
	global_load_dwordx4 v[10:13], v[136:137], off offset:576
	s_mov_b32 s98, 0x160000
	s_mov_b32 s99, 0
	v_lshl_add_u64 v[136:137], v[134:135], 0, s[98:99]
	global_load_dwordx4 v[22:25], v[136:137], off
	global_load_dwordx4 v[18:21], v[136:137], off offset:64
	global_load_dwordx4 v[6:9], v[136:137], off offset:512
	global_load_dwordx4 v[2:5], v[136:137], off offset:576
	s_waitcnt vmcnt(0)
	s_branch .LBB0_344
.Lrp_zero:
	v_mov_b32_e32 v2, 0
	v_mov_b32_e32 v3, v2
	v_mov_b32_e32 v4, v2
	v_mov_b32_e32 v5, v2
	v_mov_b32_e32 v6, v2
	v_mov_b32_e32 v7, v2
	v_mov_b32_e32 v8, v2
	v_mov_b32_e32 v9, v2
	v_mov_b32_e32 v10, v2
	v_mov_b32_e32 v11, v2
	v_mov_b32_e32 v12, v2
	v_mov_b32_e32 v13, v2
	v_mov_b32_e32 v14, v2
	v_mov_b32_e32 v15, v2
	v_mov_b32_e32 v16, v2
	v_mov_b32_e32 v17, v2
	v_mov_b32_e32 v26, v2
	v_mov_b32_e32 v27, v2
	v_mov_b32_e32 v28, v2
	v_mov_b32_e32 v29, v2
	v_mov_b32_e32 v30, v2
	v_mov_b32_e32 v31, v2
	v_mov_b32_e32 v32, v2
	v_mov_b32_e32 v33, v2
	v_mov_b32_e32 v42, v2
	v_mov_b32_e32 v43, v2
	v_mov_b32_e32 v44, v2
	v_mov_b32_e32 v45, v2
	v_mov_b32_e32 v46, v2
	v_mov_b32_e32 v47, v2
	v_mov_b32_e32 v48, v2
	v_mov_b32_e32 v49, v2
	v_mov_b32_e32 v18, v2
	v_mov_b32_e32 v19, v2
	v_mov_b32_e32 v20, v2
	v_mov_b32_e32 v21, v2
	v_mov_b32_e32 v22, v2
	v_mov_b32_e32 v23, v2
	v_mov_b32_e32 v24, v2
	v_mov_b32_e32 v25, v2
	v_mov_b32_e32 v34, v2
	v_mov_b32_e32 v35, v2
	v_mov_b32_e32 v36, v2
	v_mov_b32_e32 v37, v2
	v_mov_b32_e32 v38, v2
	v_mov_b32_e32 v39, v2
	v_mov_b32_e32 v40, v2
	v_mov_b32_e32 v41, v2
	v_mov_b32_e32 v50, v2
	v_mov_b32_e32 v51, v2
	v_mov_b32_e32 v52, v2
	v_mov_b32_e32 v53, v2
	v_mov_b32_e32 v54, v2
	v_mov_b32_e32 v55, v2
	v_mov_b32_e32 v56, v2
	v_mov_b32_e32 v57, v2
	v_mov_b32_e32 v58, v2
	v_mov_b32_e32 v59, v2
	v_mov_b32_e32 v60, v2
	v_mov_b32_e32 v61, v2
	v_mov_b32_e32 v62, v2
	v_mov_b32_e32 v63, v2
	v_mov_b32_e32 v64, v2
	v_mov_b32_e32 v65, v2
	v_mov_b32_e32 v66, v2
	v_mov_b32_e32 v67, v2
	v_mov_b32_e32 v68, v2
	v_mov_b32_e32 v69, v2
	v_mov_b32_e32 v70, v2
	v_mov_b32_e32 v71, v2
	v_mov_b32_e32 v72, v2
	v_mov_b32_e32 v73, v2
	v_mov_b32_e32 v74, v2
	v_mov_b32_e32 v75, v2
	v_mov_b32_e32 v76, v2
	v_mov_b32_e32 v77, v2
	v_mov_b32_e32 v78, v2
	v_mov_b32_e32 v79, v2
	v_mov_b32_e32 v80, v2
	v_mov_b32_e32 v81, v2
	v_mov_b32_e32 v90, v2
	v_mov_b32_e32 v91, v2
	v_mov_b32_e32 v92, v2
	v_mov_b32_e32 v93, v2
	v_mov_b32_e32 v94, v2
	v_mov_b32_e32 v95, v2
	v_mov_b32_e32 v96, v2
	v_mov_b32_e32 v97, v2
	v_mov_b32_e32 v106, v2
	v_mov_b32_e32 v107, v2
	v_mov_b32_e32 v108, v2
	v_mov_b32_e32 v109, v2
	v_mov_b32_e32 v110, v2
	v_mov_b32_e32 v111, v2
	v_mov_b32_e32 v112, v2
	v_mov_b32_e32 v113, v2
	v_mov_b32_e32 v82, v2
	v_mov_b32_e32 v83, v2
	v_mov_b32_e32 v84, v2
	v_mov_b32_e32 v85, v2
	v_mov_b32_e32 v86, v2
	v_mov_b32_e32 v87, v2
	v_mov_b32_e32 v88, v2
	v_mov_b32_e32 v89, v2
	v_mov_b32_e32 v98, v2
	v_mov_b32_e32 v99, v2
	v_mov_b32_e32 v100, v2
	v_mov_b32_e32 v101, v2
	v_mov_b32_e32 v102, v2
	v_mov_b32_e32 v103, v2
	v_mov_b32_e32 v104, v2
	v_mov_b32_e32 v105, v2
	v_mov_b32_e32 v114, v2
	v_mov_b32_e32 v115, v2
	v_mov_b32_e32 v116, v2
	v_mov_b32_e32 v117, v2
	v_mov_b32_e32 v118, v2
	v_mov_b32_e32 v119, v2
	v_mov_b32_e32 v120, v2
	v_mov_b32_e32 v121, v2
	v_mov_b32_e32 v122, v2
	v_mov_b32_e32 v123, v2
	v_mov_b32_e32 v124, v2
	v_mov_b32_e32 v125, v2
	v_mov_b32_e32 v126, v2
	v_mov_b32_e32 v127, v2
	v_mov_b32_e32 v128, v2
	v_mov_b32_e32 v129, v2

.LBB0_374:
	s_and_b64 vcc, exec, s[48:49]
	s_cbranch_vccz .LBB0_387
	v_lshl_or_b32 v202, s23, 8, v225
	s_cmp_lt_i32 s88, 0
	s_mov_b64 s[48:49], -1
	v_ashrrev_i32_e32 v203, 31, v202
	v_add_u32_e32 v204, 0xffffe000, v196
	v_add_u32_e32 v200, 0xffffe010, v196
	v_add_u32_e32 v198, 0xffffe020, v196
	s_cbranch_scc0 .LBB0_385
	v_ashrrev_i32_e32 v197, 31, v196
	v_lshlrev_b64 v[130:131], 13, v[196:197]
	v_lshl_add_u64 v[130:131], s[78:79], 0, v[130:131]
	v_lshlrev_b64 v[206:207], 2, v[202:203]
	v_lshl_add_u64 v[134:135], v[130:131], 0, v[206:207]
	global_store_dwordx4 v[134:135], v[126:129], off
	global_store_dwordx4 v[134:135], v[122:125], off offset:64
	global_store_dwordx4 v[134:135], v[110:113], off offset:512
	global_store_dwordx4 v[134:135], v[106:109], off offset:576
	s_mov_b32 s98, 0x20000
	s_mov_b32 s99, 0
	v_lshl_add_u64 v[136:137], v[134:135], 0, s[98:99]
	global_store_dwordx4 v[136:137], v[118:121], off
	global_store_dwordx4 v[136:137], v[114:117], off offset:64
	global_store_dwordx4 v[136:137], v[94:97], off offset:512
	global_store_dwordx4 v[136:137], v[90:93], off offset:576
	s_mov_b32 s98, 0x40000
	s_mov_b32 s99, 0
	v_lshl_add_u64 v[136:137], v[134:135], 0, s[98:99]
	global_store_dwordx4 v[136:137], v[102:105], off
	global_store_dwordx4 v[136:137], v[98:101], off offset:64
	global_store_dwordx4 v[136:137], v[78:81], off offset:512
	global_store_dwordx4 v[136:137], v[74:77], off offset:576
	s_mov_b32 s98, 0x60000
	s_mov_b32 s99, 0
	v_lshl_add_u64 v[136:137], v[134:135], 0, s[98:99]
	global_store_dwordx4 v[136:137], v[86:89], off
	global_store_dwordx4 v[136:137], v[82:85], off offset:64
	global_store_dwordx4 v[136:137], v[70:73], off offset:512
	global_store_dwordx4 v[136:137], v[66:69], off offset:576
	s_mov_b32 s98, 0x100000
	s_mov_b32 s99, 0
	v_lshl_add_u64 v[136:137], v[134:135], 0, s[98:99]
	global_store_dwordx4 v[136:137], v[62:65], off
	global_store_dwordx4 v[136:137], v[58:61], off offset:64
	global_store_dwordx4 v[136:137], v[46:49], off offset:512
	global_store_dwordx4 v[136:137], v[42:45], off offset:576
	s_mov_b32 s98, 0x120000
	s_mov_b32 s99, 0
	v_lshl_add_u64 v[136:137], v[134:135], 0, s[98:99]
	global_store_dwordx4 v[136:137], v[54:57], off
	global_store_dwordx4 v[136:137], v[50:53], off offset:64
	global_store_dwordx4 v[136:137], v[30:33], off offset:512
	global_store_dwordx4 v[136:137], v[26:29], off offset:576
	s_mov_b32 s98, 0x140000
	s_mov_b32 s99, 0
	v_lshl_add_u64 v[136:137], v[134:135], 0, s[98:99]
	global_store_dwordx4 v[136:137], v[38:41], off
	global_store_dwordx4 v[136:137], v[34:37], off offset:64
	global_store_dwordx4 v[136:137], v[14:17], off offset:512
	global_store_dwordx4 v[136:137], v[10:13], off offset:576
	s_mov_b32 s98, 0x160000
	s_mov_b32 s99, 0
	v_lshl_add_u64 v[136:137], v[134:135], 0, s[98:99]
	global_store_dwordx4 v[136:137], v[22:25], off
	global_store_dwordx4 v[136:137], v[18:21], off offset:64
	global_store_dwordx4 v[136:137], v[6:9], off offset:512
	global_store_dwordx4 v[136:137], v[2:5], off offset:576
	s_mov_b64 s[48:49], 0
